# DF attention: split v_pk_fma_f32 in softmax finish into scalar v_fma_f32 (on top of v14)
# speedup vs baseline: 1.0445x; 1.0004x over previous
; DI void attn_item_df2(const bf16_t* Qb, const bf16_t* Kb, size_t mstride, const bf16_t* VTb, int q0, int nkt  , float cs,
;                       bf16_t* Orow, float lam, float outscale, const float* subw, char* smem) {
;     ...
;   {
;     const f32x2_t cs2 = {cs, cs}, mc2 = {mrun * cs, mrun * cs}; f32x2_t ps2 = {0.f, 0.f};
; #pragma unroll
;     for (int st = 0; st < 8; ++st) { D2_FIN(pB, st); }
;     lrun += ps2.x + ps2.y;
;     float mxd = 0.f;
;     D2_SEG_B(pB, pB, vs0, false, false, false, 0, 0, mxd);
;   }
;   __syncthreads();
;     ...
;   lrun += __shfl_xor(lrun, 32);
.LBB0_264:
	v_mov_b32_e32 v159, v158
	v_fma_f32 v64, v112, s78, -v158
	v_fma_f32 v65, v113, s78, -v159
	v_fma_f32 v66, v114, s78, -v158
	v_fma_f32 v67, v115, s78, -v159
	v_exp_f32_e32 v64, v64
	v_exp_f32_e32 v65, v65
	v_exp_f32_e32 v66, v66
	v_exp_f32_e32 v67, v67
	v_fma_f32 v72, v118, s78, -v158
	v_fma_f32 v73, v119, s78, -v159
	v_pk_add_f32 v[70:71], v[64:65], 0 op_sel_hi:[1,0]
	v_cvt_pk_bf16_f32 v64, v64, v65
	v_pk_add_f32 v[70:71], v[66:67], v[70:71]
	v_cvt_pk_bf16_f32 v65, v66, v67
	v_fma_f32 v66, v116, s78, -v158
	v_fma_f32 v67, v117, s78, -v159
	v_exp_f32_e32 v72, v72
	v_exp_f32_e32 v66, v66
	v_exp_f32_e32 v67, v67
	v_exp_f32_e32 v73, v73
	v_fma_f32 v74, v122, s78, -v158
	v_fma_f32 v75, v123, s78, -v159
	v_fma_f32 v78, v98, s78, -v158
	v_fma_f32 v79, v99, s78, -v159
	v_pk_add_f32 v[70:71], v[66:67], v[70:71]
	v_cvt_pk_bf16_f32 v66, v66, v67
	v_pk_add_f32 v[70:71], v[72:73], v[70:71]
	v_cvt_pk_bf16_f32 v67, v72, v73
	v_fma_f32 v72, v120, s78, -v158
	v_fma_f32 v73, v121, s78, -v159
	v_exp_f32_e32 v74, v74
	v_exp_f32_e32 v72, v72
	v_exp_f32_e32 v73, v73
	v_exp_f32_e32 v75, v75
	v_exp_f32_e32 v78, v78
	v_exp_f32_e32 v79, v79
	v_pk_add_f32 v[70:71], v[72:73], v[70:71]
	v_fma_f32 v80, v102, s78, -v158
	v_fma_f32 v81, v103, s78, -v159
	v_pk_add_f32 v[76:77], v[74:75], v[70:71]
	v_cvt_pk_bf16_f32 v70, v72, v73
	v_fma_f32 v72, v124, s78, -v158
	v_fma_f32 v73, v125, s78, -v159
	v_cvt_pk_bf16_f32 v71, v74, v75
	v_fma_f32 v74, v126, s78, -v158
	v_fma_f32 v75, v127, s78, -v159
	v_exp_f32_e32 v72, v72
	v_exp_f32_e32 v73, v73
	v_exp_f32_e32 v74, v74
	v_exp_f32_e32 v75, v75
	v_exp_f32_e32 v80, v80
	v_pk_add_f32 v[76:77], v[72:73], v[76:77]
	v_cvt_pk_bf16_f32 v72, v72, v73
	v_pk_add_f32 v[76:77], v[74:75], v[76:77]
	v_cvt_pk_bf16_f32 v73, v74, v75
	v_fma_f32 v74, v96, s78, -v158
	v_fma_f32 v75, v97, s78, -v159
	v_exp_f32_e32 v81, v81
	v_exp_f32_e32 v74, v74
	v_exp_f32_e32 v75, v75
	v_fma_f32 v84, v110, s78, -v158
	v_fma_f32 v85, v111, s78, -v159
	s_waitcnt lgkmcnt(0)
	v_exp_f32_e32 v84, v84
	v_pk_add_f32 v[76:77], v[74:75], v[76:77]
	v_cvt_pk_bf16_f32 v74, v74, v75
	v_pk_add_f32 v[76:77], v[78:79], v[76:77]
	v_cvt_pk_bf16_f32 v75, v78, v79
	v_fma_f32 v78, v100, s78, -v158
	v_fma_f32 v79, v101, s78, -v159
	v_exp_f32_e32 v85, v85
	v_exp_f32_e32 v78, v78
	v_exp_f32_e32 v79, v79
	s_barrier
	v_pk_add_f32 v[76:77], v[78:79], v[76:77]
	s_nop 0
	v_pk_add_f32 v[82:83], v[80:81], v[76:77]
	v_cvt_pk_bf16_f32 v76, v78, v79
	v_fma_f32 v78, v104, s78, -v158
	v_fma_f32 v79, v105, s78, -v159
	v_cvt_pk_bf16_f32 v77, v80, v81
	v_fma_f32 v80, v106, s78, -v158
	v_fma_f32 v81, v107, s78, -v159
	v_exp_f32_e32 v78, v78
	v_exp_f32_e32 v79, v79
	v_exp_f32_e32 v80, v80
	v_exp_f32_e32 v81, v81
	v_pk_add_f32 v[82:83], v[78:79], v[82:83]
	v_cvt_pk_bf16_f32 v78, v78, v79
	v_pk_add_f32 v[82:83], v[80:81], v[82:83]
	v_cvt_pk_bf16_f32 v79, v80, v81
	v_fma_f32 v80, v108, s78, -v158
	v_fma_f32 v81, v109, s78, -v159
	s_nop 0
	v_exp_f32_e32 v80, v80
	v_exp_f32_e32 v81, v81
	s_nop 0
	v_pk_add_f32 v[82:83], v[80:81], v[82:83]
	s_nop 0
	v_pk_add_f32 v[98:99], v[84:85], v[82:83]
	v_cvt_pk_bf16_f32 v80, v80, v81
	v_cvt_pk_bf16_f32 v81, v84, v85
	ds_read_b128 v[82:85], v160 offset:36864
	ds_read_b128 v[86:89], v160 offset:41472
	ds_read_b128 v[90:93], v160 offset:46080
	ds_read_b128 v[94:97], v160 offset:50688
	v_add_f32_e32 v69, v98, v99
	ds_read_b128 v[98:101], v160 offset:36896
	ds_read_b128 v[102:105], v160 offset:41504
	ds_read_b128 v[106:109], v160 offset:46112
	ds_read_b128 v[110:113], v160 offset:50720
	s_waitcnt lgkmcnt(7)
	v_mfma_f32_32x32x16_bf16 v[16:31], v[82:85], v[64:67], v[16:31]
	s_waitcnt lgkmcnt(6)
	v_mfma_f32_32x32x16_bf16 v[48:63], v[86:89], v[64:67], v[48:63]
	s_waitcnt lgkmcnt(5)
	v_mfma_f32_32x32x16_bf16 v[32:47], v[90:93], v[64:67], v[32:47]
	s_waitcnt lgkmcnt(4)
	v_mfma_f32_32x32x16_bf16 v[0:15], v[94:97], v[64:67], v[0:15]
	ds_read_b128 v[64:67], v160 offset:36928
	ds_read_b128 v[82:85], v160 offset:41536
	ds_read_b128 v[86:89], v160 offset:46144
	ds_read_b128 v[90:93], v160 offset:50752
	s_waitcnt lgkmcnt(7)
	v_mfma_f32_32x32x16_bf16 v[16:31], v[98:101], v[70:73], v[16:31]
	s_waitcnt lgkmcnt(6)
	v_mfma_f32_32x32x16_bf16 v[48:63], v[102:105], v[70:73], v[48:63]
	s_waitcnt lgkmcnt(5)
	v_mfma_f32_32x32x16_bf16 v[32:47], v[106:109], v[70:73], v[32:47]
	s_waitcnt lgkmcnt(4)
	v_mfma_f32_32x32x16_bf16 v[0:15], v[110:113], v[70:73], v[0:15]
	ds_read_b128 v[70:73], v160 offset:36960
	ds_read_b128 v[94:97], v160 offset:41568
	ds_read_b128 v[98:101], v160 offset:46176
	ds_read_b128 v[102:105], v160 offset:50784
	s_waitcnt lgkmcnt(7)
	v_mfma_f32_32x32x16_bf16 v[16:31], v[64:67], v[74:77], v[16:31]
	s_waitcnt lgkmcnt(6)
	v_mfma_f32_32x32x16_bf16 v[48:63], v[82:85], v[74:77], v[48:63]
	s_waitcnt lgkmcnt(5)
	v_mfma_f32_32x32x16_bf16 v[32:47], v[86:89], v[74:77], v[32:47]
	s_waitcnt lgkmcnt(4)
	v_mfma_f32_32x32x16_bf16 v[0:15], v[90:93], v[74:77], v[0:15]
	s_waitcnt lgkmcnt(3)
	v_mfma_f32_32x32x16_bf16 v[16:31], v[70:73], v[78:81], v[16:31]
	v_add_f32_e32 v64, v68, v69
	s_waitcnt lgkmcnt(2)
	v_mfma_f32_32x32x16_bf16 v[48:63], v[94:97], v[78:81], v[48:63]
	s_waitcnt lgkmcnt(1)
	v_mfma_f32_32x32x16_bf16 v[32:47], v[98:101], v[78:81], v[32:47]
	s_waitcnt lgkmcnt(0)
	v_mfma_f32_32x32x16_bf16 v[0:15], v[102:105], v[78:81], v[0:15]
	v_and_b32_e32 v66, 64, v200
	v_xor_b32_e32 v65, 32, v200
	v_add_u32_e32 v66, 64, v66
	v_cmp_lt_i32_e32 vcc, v65, v66
	s_barrier
; DI void attn_item_df2(const bf16_t* Qb, const bf16_t* Kb, size_t mstride, const bf16_t* VTb, int q0, int nkt  , float cs,
;                       bf16_t* Orow, float lam, float outscale, const float* subw, char* smem) {
;     ...
;   lrun += __shfl_xor(lrun, 32);
;   const float inv = 1.f / lrun;
; #pragma unroll
;   for (int db = 0; db < 4; ++db)
; #pragma unroll
;     for (int i = 0; i < 16; ++i) oacc[db][i] *= inv;
;   float* cb = (float*)smem;
;   if (m == 1) {
; #pragma unroll
;     for (int db = 0; db < 4; ++db)
; #pragma unroll
;       for (int i = 0; i < 16; ++i) cb[(wq * 64 + db * 16 + i) * 64 + lane] = oacc[db][i];
;   }
	s_nop 0
	v_cndmask_b32_e32 v65, v200, v65, vcc
	v_lshlrev_b32_e32 v94, 2, v65
	ds_bpermute_b32 v65, v94, v64
	s_waitcnt lgkmcnt(0)
	v_add_f32_e32 v64, v64, v65
	v_div_scale_f32 v65, s[0:1], v64, v64, 1.0
	v_rcp_f32_e32 v66, v65
	s_nop 0
	v_fma_f32 v67, -v65, v66, 1.0
	v_fmac_f32_e32 v66, v67, v66
	v_div_scale_f32 v67, vcc, 1.0, v64, 1.0
	v_mul_f32_e32 v68, v67, v66
	v_fma_f32 v69, -v65, v68, v67
	v_fmac_f32_e32 v68, v69, v66
	v_fma_f32 v65, -v65, v68, v67
	v_div_fmas_f32 v65, v65, v66, v68
	v_div_fixup_f32 v80, v65, v64, 1.0
	v_pk_mul_f32 v[64:65], v[16:17], v[80:81] op_sel_hi:[1,0]
	v_pk_mul_f32 v[66:67], v[18:19], v[80:81] op_sel_hi:[1,0]
	v_pk_mul_f32 v[68:69], v[20:21], v[80:81] op_sel_hi:[1,0]
	v_pk_mul_f32 v[70:71], v[22:23], v[80:81] op_sel_hi:[1,0]
	v_pk_mul_f32 v[72:73], v[24:25], v[80:81] op_sel_hi:[1,0]
	v_pk_mul_f32 v[74:75], v[26:27], v[80:81] op_sel_hi:[1,0]
	v_pk_mul_f32 v[76:77], v[28:29], v[80:81] op_sel_hi:[1,0]
	v_pk_mul_f32 v[78:79], v[30:31], v[80:81] op_sel_hi:[1,0]
	v_pk_mul_f32 v[20:21], v[48:49], v[80:81] op_sel_hi:[1,0]
	v_pk_mul_f32 v[22:23], v[50:51], v[80:81] op_sel_hi:[1,0]
	v_pk_mul_f32 v[28:29], v[52:53], v[80:81] op_sel_hi:[1,0]
	v_pk_mul_f32 v[48:49], v[54:55], v[80:81] op_sel_hi:[1,0]
	v_pk_mul_f32 v[52:53], v[56:57], v[80:81] op_sel_hi:[1,0]
	v_pk_mul_f32 v[56:57], v[58:59], v[80:81] op_sel_hi:[1,0]
	v_pk_mul_f32 v[58:59], v[60:61], v[80:81] op_sel_hi:[1,0]
	v_pk_mul_f32 v[60:61], v[62:63], v[80:81] op_sel_hi:[1,0]
	v_pk_mul_f32 v[16:17], v[32:33], v[80:81] op_sel_hi:[1,0]
	v_pk_mul_f32 v[26:27], v[34:35], v[80:81] op_sel_hi:[1,0]
	v_pk_mul_f32 v[34:35], v[36:37], v[80:81] op_sel_hi:[1,0]
	v_pk_mul_f32 v[32:33], v[38:39], v[80:81] op_sel_hi:[1,0]
	v_pk_mul_f32 v[30:31], v[40:41], v[80:81] op_sel_hi:[1,0]
	v_pk_mul_f32 v[50:51], v[42:43], v[80:81] op_sel_hi:[1,0]
	v_pk_mul_f32 v[54:55], v[44:45], v[80:81] op_sel_hi:[1,0]
	v_pk_mul_f32 v[46:47], v[46:47], v[80:81] op_sel_hi:[1,0]
	v_pk_mul_f32 v[18:19], v[0:1], v[80:81] op_sel_hi:[1,0]
	v_pk_mul_f32 v[24:25], v[2:3], v[80:81] op_sel_hi:[1,0]
	v_pk_mul_f32 v[38:39], v[4:5], v[80:81] op_sel_hi:[1,0]
	v_pk_mul_f32 v[42:43], v[6:7], v[80:81] op_sel_hi:[1,0]
	v_pk_mul_f32 v[44:45], v[8:9], v[80:81] op_sel_hi:[1,0]
	v_pk_mul_f32 v[10:11], v[10:11], v[80:81] op_sel_hi:[1,0]
	v_pk_mul_f32 v[2:3], v[12:13], v[80:81] op_sel_hi:[1,0]
	v_pk_mul_f32 v[0:1], v[14:15], v[80:81] op_sel_hi:[1,0]
	v_cmp_eq_u32_e32 vcc, 1, v214
	s_and_saveexec_b64 s[0:1], vcc
	s_cbranch_execz .LBB0_266
	v_lshlrev_b32_e32 v4, 14, v169
	v_lshlrev_b32_e32 v5, 2, v179
	v_add3_u32 v4, 0, v5, v4
	ds_write2st64_b32 v4, v64, v65 offset1:1
	ds_write2st64_b32 v4, v66, v67 offset0:2 offset1:3
	ds_write2st64_b32 v4, v68, v69 offset0:4 offset1:5
	ds_write2st64_b32 v4, v70, v71 offset0:6 offset1:7
	ds_write2st64_b32 v4, v72, v73 offset0:8 offset1:9
	ds_write2st64_b32 v4, v74, v75 offset0:10 offset1:11
	ds_write2st64_b32 v4, v76, v77 offset0:12 offset1:13
	ds_write2st64_b32 v4, v78, v79 offset0:14 offset1:15
	ds_write2st64_b32 v4, v20, v21 offset0:16 offset1:17
	ds_write2st64_b32 v4, v22, v23 offset0:18 offset1:19
	ds_write2st64_b32 v4, v28, v29 offset0:20 offset1:21
	ds_write2st64_b32 v4, v48, v49 offset0:22 offset1:23
	ds_write2st64_b32 v4, v52, v53 offset0:24 offset1:25
	ds_write2st64_b32 v4, v56, v57 offset0:26 offset1:27
	ds_write2st64_b32 v4, v58, v59 offset0:28 offset1:29
	ds_write2st64_b32 v4, v60, v61 offset0:30 offset1:31
	ds_write2st64_b32 v4, v16, v17 offset0:32 offset1:33
	ds_write2st64_b32 v4, v26, v27 offset0:34 offset1:35
	ds_write2st64_b32 v4, v34, v35 offset0:36 offset1:37
	ds_write2st64_b32 v4, v32, v33 offset0:38 offset1:39
	ds_write2st64_b32 v4, v30, v31 offset0:40 offset1:41
	ds_write2st64_b32 v4, v50, v51 offset0:42 offset1:43
	ds_write2st64_b32 v4, v54, v55 offset0:44 offset1:45
	ds_write2st64_b32 v4, v46, v47 offset0:46 offset1:47
	ds_write2st64_b32 v4, v18, v19 offset0:48 offset1:49
	ds_write2st64_b32 v4, v24, v25 offset0:50 offset1:51
	ds_write2st64_b32 v4, v38, v39 offset0:52 offset1:53
	ds_write2st64_b32 v4, v42, v43 offset0:54 offset1:55
	ds_write2st64_b32 v4, v44, v45 offset0:56 offset1:57
	ds_write2st64_b32 v4, v10, v11 offset0:58 offset1:59
	ds_write2st64_b32 v4, v2, v3 offset0:60 offset1:61
	ds_write2st64_b32 v4, v0, v1 offset0:62 offset1:63
; DI void attn_item_df2(const bf16_t* Qb, const bf16_t* Kb, size_t mstride, const bf16_t* VTb, int q0, int nkt  , float cs,
;                       bf16_t* Orow, float lam, float outscale, const float* subw, char* smem) {
;     ...
;   __syncthreads();
;   if (m == 0) {
;     float ss = 0.f;
; #pragma unroll
;     for (int db = 0; db < 4; ++db)
; #pragma unroll
;       for (int i = 0; i < 16; ++i) { float o = oacc[db][i] - lam * cb[(wq * 64 + db * 16 + i) * 64 + lane]; oacc[db][i] = o; ss += o * o; }
;     ss += __shfl_xor(ss, 32);
.LBB0_266:
	s_or_b64 exec, exec, s[0:1]
	s_movk_i32 s0, 0x100
	v_cmp_gt_u32_e32 vcc, s0, v165
	s_waitcnt lgkmcnt(0)
	s_barrier
	s_and_saveexec_b64 s[0:1], vcc
	s_cbranch_execz .LBB0_255
	v_lshlrev_b32_e32 v9, 8, v165
	v_lshl_add_u32 v8, v179, 2, 0
	v_and_b32_e32 v4, 0xc000, v9
	v_add_u32_e32 v88, v8, v4
	ds_read2st64_b32 v[36:37], v88 offset1:1
	ds_read2st64_b32 v[40:41], v88 offset0:2 offset1:3
	ds_read2st64_b32 v[100:101], v88 offset0:4 offset1:5
	ds_read2st64_b32 v[102:103], v88 offset0:6 offset1:7
	ds_read2st64_b32 v[104:105], v88 offset0:8 offset1:9
	ds_read2st64_b32 v[96:97], v88 offset0:10 offset1:11
	ds_read2st64_b32 v[98:99], v88 offset0:12 offset1:13
	ds_read2st64_b32 v[106:107], v88 offset0:14 offset1:15
	ds_read2st64_b32 v[86:87], v88 offset0:16 offset1:17
	ds_read2st64_b32 v[108:109], v88 offset0:18 offset1:19
	ds_read2st64_b32 v[110:111], v88 offset0:20 offset1:21
	ds_read2st64_b32 v[112:113], v88 offset0:22 offset1:23
	ds_read2st64_b32 v[114:115], v88 offset0:24 offset1:25
	ds_read2st64_b32 v[116:117], v88 offset0:26 offset1:27
	ds_read2st64_b32 v[118:119], v88 offset0:28 offset1:29
	ds_read2st64_b32 v[120:121], v88 offset0:30 offset1:31
	ds_read2st64_b32 v[12:13], v88 offset0:32 offset1:33
	ds_read2st64_b32 v[14:15], v88 offset0:34 offset1:35
	ds_read2st64_b32 v[92:93], v88 offset0:36 offset1:37
	ds_read2st64_b32 v[122:123], v88 offset0:38 offset1:39
	ds_read2st64_b32 v[124:125], v88 offset0:40 offset1:41
	ds_read2st64_b32 v[126:127], v88 offset0:42 offset1:43
	ds_read2st64_b32 v[128:129], v88 offset0:44 offset1:45
	ds_read2st64_b32 v[130:131], v88 offset0:46 offset1:47
	ds_read2st64_b32 v[80:81], v88 offset0:48 offset1:49
	ds_read2st64_b32 v[82:83], v88 offset0:50 offset1:51
	ds_read2st64_b32 v[84:85], v88 offset0:52 offset1:53
	ds_read2st64_b32 v[90:91], v88 offset0:54 offset1:55
	ds_read2st64_b32 v[132:133], v88 offset0:56 offset1:57
	ds_read2st64_b32 v[134:135], v88 offset0:58 offset1:59
	ds_read2st64_b32 v[4:5], v88 offset0:60 offset1:61
	v_readlane_b32 s56, v254, 45
	s_waitcnt lgkmcnt(14)
	v_fma_f32 v64, -v162, v36, v64
	v_fma_f32 v65, -v163, v37, v65
	v_readlane_b32 s66, v254, 55
	v_readlane_b32 s67, v254, 56
	s_waitcnt lgkmcnt(0)
	v_fma_f32 v6, -v162, v4, v2
	v_fma_f32 v7, -v163, v5, v3
	v_or_b32_e32 v3, 0x3f00, v9
	v_fma_f32 v148, -v162, v40, v66
	v_fma_f32 v149, -v163, v41, v67
	v_pk_mul_f32 v[152:153], v[64:65], v[64:65]
	v_add_u32_e32 v3, v8, v3
	v_fma_f32 v104, -v162, v104, v72
	v_fma_f32 v105, -v163, v105, v73
	v_fma_f32 v102, -v162, v102, v70
	v_fma_f32 v103, -v163, v103, v71
	global_load_dwordx4 v[70:73], v140, s[66:67] offset:32
	v_fma_f32 v100, -v162, v100, v68
	v_fma_f32 v101, -v163, v101, v69
	v_pk_mul_f32 v[150:151], v[148:149], v[148:149]
	global_load_dwordx4 v[66:69], v140, s[66:67]
	v_fma_f32 v86, -v162, v86, v20
	v_fma_f32 v87, -v163, v87, v21
	v_fma_f32 v20, -v162, v130, v46
	v_fma_f32 v21, -v163, v131, v47
	v_fma_f32 v46, -v162, v14, v26
	v_fma_f32 v47, -v163, v15, v27
	v_fma_f32 v26, -v162, v80, v18
	v_fma_f32 v27, -v163, v81, v19
	v_add_f32_e32 v80, v152, v153
	ds_read_b32 v2, v88 offset:15872
	ds_read_b32 v3, v3
	v_add_f32_e32 v80, v80, v150
	v_pk_mul_f32 v[146:147], v[100:101], v[100:101]
	v_add_f32_e32 v80, v80, v151
	s_ashr_i32 s3, s36, 6
	v_add_f32_e32 v80, v80, v146
	s_mul_hi_i32 s24, s3, 0x1080000
	s_mul_i32 s3, s3, 0x1080000
	v_pk_mul_f32 v[144:145], v[102:103], v[102:103]
	v_add_f32_e32 v80, v80, v147
	s_add_u32 s28, s40, s3
	v_add_f32_e32 v80, v80, v144
	s_addc_u32 s29, s41, s24
	s_waitcnt lgkmcnt(0)
	v_fma_f32 v8, -v162, v2, v0
	v_fma_f32 v9, -v163, v3, v1
	v_lshlrev_b32_e32 v0, 11, v164
	v_mov_b32_e32 v1, v141
	v_pk_mul_f32 v[142:143], v[104:105], v[104:105]
	v_add_f32_e32 v80, v80, v145
	v_lshl_add_u64 v[0:1], s[28:29], 0, v[0:1]
	v_lshlrev_b32_e32 v2, 1, v168
	v_mov_b32_e32 v3, v141
	v_fma_f32 v74, -v162, v96, v74
	v_fma_f32 v75, -v163, v97, v75
	v_add_f32_e32 v80, v80, v142
	v_lshl_add_u64 v[4:5], v[0:1], 0, v[2:3]
	global_load_dwordx4 v[0:3], v140, s[66:67] offset:96
	v_fma_f32 v76, -v162, v98, v76
	v_fma_f32 v77, -v163, v99, v77
	v_pk_mul_f32 v[138:139], v[74:75], v[74:75]
	global_load_dwordx4 v[96:99], v140, s[66:67] offset:64
	v_add_f32_e32 v80, v80, v143
	v_add_f32_e32 v80, v80, v138
	v_pk_mul_f32 v[136:137], v[76:77], v[76:77]
	v_add_f32_e32 v80, v80, v139
	v_fma_f32 v78, -v162, v106, v78
	v_fma_f32 v79, -v163, v107, v79
	v_add_f32_e32 v80, v80, v136
	v_pk_mul_f32 v[106:107], v[78:79], v[78:79]
	v_add_f32_e32 v80, v80, v137
	v_add_f32_e32 v80, v80, v106
	v_pk_mul_f32 v[156:157], v[86:87], v[86:87]
	v_add_f32_e32 v80, v80, v107
	v_fma_f32 v108, -v162, v108, v22
	v_fma_f32 v109, -v163, v109, v23
	v_add_f32_e32 v80, v80, v156
	v_pk_mul_f32 v[154:155], v[108:109], v[108:109]
	v_add_f32_e32 v80, v80, v157
	v_fma_f32 v36, -v162, v120, v60
	v_fma_f32 v37, -v163, v121, v61
	v_fma_f32 v60, -v162, v110, v28
	v_fma_f32 v61, -v163, v111, v29
	v_add_f32_e32 v80, v80, v154
	v_pk_mul_f32 v[110:111], v[60:61], v[60:61]
	v_add_f32_e32 v80, v80, v155
	v_fma_f32 v40, -v162, v118, v58
	v_fma_f32 v41, -v163, v119, v59
	v_fma_f32 v58, -v162, v112, v48
	v_fma_f32 v59, -v163, v113, v49
	v_add_f32_e32 v80, v80, v110
	v_pk_mul_f32 v[112:113], v[58:59], v[58:59]
	v_add_f32_e32 v80, v80, v111
	v_fma_f32 v52, -v162, v114, v52
	v_fma_f32 v53, -v163, v115, v53
	v_add_f32_e32 v80, v80, v112
	v_pk_mul_f32 v[114:115], v[52:53], v[52:53]
	v_add_f32_e32 v80, v80, v113
	v_fma_f32 v56, -v162, v116, v56
	v_fma_f32 v57, -v163, v117, v57
	v_add_f32_e32 v80, v80, v114
	v_pk_mul_f32 v[116:117], v[56:57], v[56:57]
	v_add_f32_e32 v80, v80, v115
	v_add_f32_e32 v80, v80, v116
	v_pk_mul_f32 v[118:119], v[40:41], v[40:41]
; DI unsigned pk2(float a, float b) { f32x2_t v = {a, b}; bf16x2_t r = __builtin_convertvector(v, bf16x2_t); return __builtin_bit_cast(unsigned, r); }
; DI void attn_item_df2(const bf16_t* Qb, const bf16_t* Kb, size_t mstride, const bf16_t* VTb, int q0, int nkt  , float cs,
;                       bf16_t* Orow, float lam, float outscale, const float* subw, char* smem) {
;     ...
;     float ss = 0.f;
; #pragma unroll
;     for (int db = 0; db < 4; ++db)
; #pragma unroll
;       for (int i = 0; i < 16; ++i) { float o = oacc[db][i] - lam * cb[(wq * 64 + db * 16 + i) * 64 + lane]; oacc[db][i] = o; ss += o * o; }
;     ss += __shfl_xor(ss, 32);
;     const float rs = rsqrtf(ss * (1.f / 128.f) + EPS) * outscale;
; #pragma unroll
;     for (int db = 0; db < 4; ++db) {
;       uint2 o[4];
; #pragma unroll
;       for (int g = 0; g < 4; ++g) {
;         int d = db * 32 + 8 * g + 4 * hh;
;         float4 w4 = *(const float4*)(subw + d);
;         o[g].x = pk2(oacc[db][4 * g] * rs * w4.x, oacc[db][4 * g + 1] * rs * w4.y);
;         o[g].y = pk2(oacc[db][4 * g + 2] * rs * w4.z, oacc[db][4 * g + 3] * rs * w4.w);
;       }
;       store_block32_packed(o, Orow + (size_t)qp * DM + db * 32, hh);
	v_add_f32_e32 v80, v80, v117
	v_add_f32_e32 v80, v80, v118
	v_pk_mul_f32 v[120:121], v[36:37], v[36:37]
	v_add_f32_e32 v80, v80, v119
	v_fma_f32 v48, -v162, v12, v16
	v_fma_f32 v49, -v163, v13, v17
	v_add_f32_e32 v80, v80, v120
	v_fma_f32 v22, -v162, v128, v54
	v_fma_f32 v23, -v163, v129, v55
	v_pk_mul_f32 v[128:129], v[48:49], v[48:49]
	v_add_f32_e32 v80, v80, v121
	v_add_f32_e32 v80, v80, v128
	v_fma_f32 v28, -v162, v126, v50
	v_fma_f32 v29, -v163, v127, v51
	v_pk_mul_f32 v[126:127], v[46:47], v[46:47]
	v_add_f32_e32 v80, v80, v129
	v_fma_f32 v34, -v162, v92, v34
	v_fma_f32 v35, -v163, v93, v35
	v_add_f32_e32 v80, v80, v126
	v_pk_mul_f32 v[92:93], v[34:35], v[34:35]
	v_add_f32_e32 v80, v80, v127
	v_fma_f32 v32, -v162, v122, v32
	v_fma_f32 v33, -v163, v123, v33
	v_add_f32_e32 v80, v80, v92
	v_pk_mul_f32 v[122:123], v[32:33], v[32:33]
	v_add_f32_e32 v80, v80, v93
	v_fma_f32 v30, -v162, v124, v30
	v_fma_f32 v31, -v163, v125, v31
	v_add_f32_e32 v80, v80, v122
	v_pk_mul_f32 v[124:125], v[30:31], v[30:31]
	v_add_f32_e32 v80, v80, v123
	v_add_f32_e32 v80, v80, v124
	v_pk_mul_f32 v[50:51], v[28:29], v[28:29]
	v_add_f32_e32 v80, v80, v125
	v_add_f32_e32 v50, v80, v50
	v_pk_mul_f32 v[54:55], v[22:23], v[22:23]
	v_add_f32_e32 v50, v50, v51
	v_add_f32_e32 v50, v50, v54
	v_pk_mul_f32 v[130:131], v[20:21], v[20:21]
	v_add_f32_e32 v50, v50, v55
	v_add_f32_e32 v50, v50, v130
	v_pk_mul_f32 v[18:19], v[26:27], v[26:27]
	v_add_f32_e32 v50, v50, v131
	v_fma_f32 v24, -v162, v82, v24
	v_fma_f32 v25, -v163, v83, v25
	v_add_f32_e32 v18, v50, v18
	v_pk_mul_f32 v[82:83], v[24:25], v[24:25]
	v_add_f32_e32 v18, v18, v19
	v_fma_f32 v16, -v162, v84, v38
	v_fma_f32 v17, -v163, v85, v39
	v_add_f32_e32 v18, v18, v82
	v_pk_mul_f32 v[38:39], v[16:17], v[16:17]
	v_add_f32_e32 v18, v18, v83
	v_fma_f32 v14, -v162, v90, v42
	v_fma_f32 v15, -v163, v91, v43
	v_add_f32_e32 v18, v18, v38
	v_pk_mul_f32 v[42:43], v[14:15], v[14:15]
	v_add_f32_e32 v18, v18, v39
	v_fma_f32 v12, -v162, v132, v44
	v_fma_f32 v13, -v163, v133, v45
	v_add_f32_e32 v18, v18, v42
	v_pk_mul_f32 v[44:45], v[12:13], v[12:13]
	v_add_f32_e32 v18, v18, v43
	v_fma_f32 v10, -v162, v134, v10
	v_fma_f32 v11, -v163, v135, v11
	v_add_f32_e32 v18, v18, v44
	v_pk_mul_f32 v[134:135], v[10:11], v[10:11]
	v_add_f32_e32 v18, v18, v45
	v_add_f32_e32 v18, v18, v134
	v_pk_mul_f32 v[62:63], v[6:7], v[6:7]
	v_add_f32_e32 v18, v18, v135
	v_add_f32_e32 v18, v18, v62
	v_pk_mul_f32 v[88:89], v[8:9], v[8:9]
	v_add_f32_e32 v18, v18, v63
	v_add_f32_e32 v18, v18, v88
	v_add_f32_e32 v18, v18, v89
	ds_bpermute_b32 v19, v94, v18
	s_mov_b32 s3, 0x800000
	v_readlane_b32 s57, v254, 46
	v_readlane_b32 s58, v254, 47
	v_readlane_b32 s59, v254, 48
	s_waitcnt lgkmcnt(0)
	v_add_f32_e32 v18, v18, v19
	v_fmamk_f32 v18, v18, 0x3c000000, v166
	v_cmp_gt_f32_e32 vcc, s3, v18
	v_mul_f32_e32 v19, 0x4b800000, v18
	v_readlane_b32 s60, v254, 49
	v_cndmask_b32_e32 v18, v18, v19, vcc
	v_rsq_f32_e32 v18, v18
	v_readlane_b32 s61, v254, 50
	v_readlane_b32 s62, v254, 51
	v_readlane_b32 s63, v254, 52
	v_mul_f32_e32 v19, 0x45800000, v18
	v_cndmask_b32_e32 v18, v18, v19, vcc
	v_mul_f32_e32 v18, 0x3f077f5a, v18
	v_pk_mul_f32 v[38:39], v[64:65], v[18:19] op_sel_hi:[1,0]
	v_pk_mul_f32 v[40:41], v[40:41], v[18:19] op_sel_hi:[1,0]
	s_waitcnt vmcnt(2)
	v_pk_mul_f32 v[38:39], v[66:67], v[38:39]
	v_pk_mul_f32 v[36:37], v[36:37], v[18:19] op_sel_hi:[1,0]
	v_cvt_pk_bf16_f32 v42, v38, v39
	v_pk_mul_f32 v[38:39], v[148:149], v[18:19] op_sel_hi:[1,0]
	v_pk_mul_f32 v[32:33], v[32:33], v[18:19] op_sel_hi:[1,0]
	v_pk_mul_f32 v[38:39], v[68:69], v[38:39]
	v_pk_mul_f32 v[30:31], v[30:31], v[18:19] op_sel_hi:[1,0]
	v_cvt_pk_bf16_f32 v43, v38, v39
	v_pk_mul_f32 v[38:39], v[100:101], v[18:19] op_sel_hi:[1,0]
	v_pk_mul_f32 v[28:29], v[28:29], v[18:19] op_sel_hi:[1,0]
	v_pk_mul_f32 v[38:39], v[70:71], v[38:39]
	v_pk_mul_f32 v[22:23], v[22:23], v[18:19] op_sel_hi:[1,0]
	v_cvt_pk_bf16_f32 v44, v38, v39
	v_pk_mul_f32 v[38:39], v[102:103], v[18:19] op_sel_hi:[1,0]
	s_nop 0
	v_permlane32_swap_b32_e32 v42, v44
	v_pk_mul_f32 v[38:39], v[72:73], v[38:39]
	v_pk_mul_f32 v[20:21], v[20:21], v[18:19] op_sel_hi:[1,0]
	v_cvt_pk_bf16_f32 v45, v38, v39
	v_pk_mul_f32 v[38:39], v[104:105], v[18:19] op_sel_hi:[1,0]
	s_nop 0
	v_permlane32_swap_b32_e32 v43, v45
	s_waitcnt vmcnt(0)
; DI unsigned pk2(float a, float b) { f32x2_t v = {a, b}; bf16x2_t r = __builtin_convertvector(v, bf16x2_t); return __builtin_bit_cast(unsigned, r); }
; DI void attn_item_df2(const bf16_t* Qb, const bf16_t* Kb, size_t mstride, const bf16_t* VTb, int q0, int nkt  , float cs,
;                       bf16_t* Orow, float lam, float outscale, const float* subw, char* smem) {
;     ...
;     for (int db = 0; db < 4; ++db) {
;       uint2 o[4];
; #pragma unroll
;       for (int g = 0; g < 4; ++g) {
;         int d = db * 32 + 8 * g + 4 * hh;
;         float4 w4 = *(const float4*)(subw + d);
;         o[g].x = pk2(oacc[db][4 * g] * rs * w4.x, oacc[db][4 * g + 1] * rs * w4.y);
;         o[g].y = pk2(oacc[db][4 * g + 2] * rs * w4.z, oacc[db][4 * g + 3] * rs * w4.w);
;       }
;       store_block32_packed(o, Orow + (size_t)qp * DM + db * 32, hh);
;     }
	v_pk_mul_f32 v[38:39], v[96:97], v[38:39]
	global_store_dwordx4 v[4:5], v[42:45], off
	v_cvt_pk_bf16_f32 v62, v38, v39
	v_pk_mul_f32 v[38:39], v[74:75], v[18:19] op_sel_hi:[1,0]
	v_pk_mul_f32 v[14:15], v[14:15], v[18:19] op_sel_hi:[1,0]
	v_pk_mul_f32 v[38:39], v[98:99], v[38:39]
	v_pk_mul_f32 v[12:13], v[12:13], v[18:19] op_sel_hi:[1,0]
	v_cvt_pk_bf16_f32 v63, v38, v39
	v_pk_mul_f32 v[38:39], v[76:77], v[18:19] op_sel_hi:[1,0]
	v_pk_mul_f32 v[10:11], v[10:11], v[18:19] op_sel_hi:[1,0]
	v_pk_mul_f32 v[0:1], v[0:1], v[38:39]
	v_pk_mul_f32 v[38:39], v[86:87], v[18:19] op_sel_hi:[1,0]
	v_cvt_pk_bf16_f32 v64, v0, v1
	v_pk_mul_f32 v[0:1], v[78:79], v[18:19] op_sel_hi:[1,0]
	s_nop 0
	v_permlane32_swap_b32_e32 v62, v64
	v_pk_mul_f32 v[0:1], v[0:1], v[2:3]
	v_pk_mul_f32 v[6:7], v[6:7], v[18:19] op_sel_hi:[1,0]
	v_cvt_pk_bf16_f32 v65, v0, v1
	s_nop 1
	v_permlane32_swap_b32_e32 v63, v65
	global_store_dwordx4 v[4:5], v[62:65], off offset:32
	global_load_dwordx4 v[0:3], v140, s[66:67] offset:128
	global_load_dwordx4 v[42:45], v140, s[66:67] offset:160
	v_readlane_b32 s64, v254, 53
	v_readlane_b32 s65, v254, 54
	v_readlane_b32 s68, v254, 57
	v_readlane_b32 s69, v254, 58
	v_readlane_b32 s70, v254, 59
	v_readlane_b32 s71, v254, 60
	s_waitcnt vmcnt(1)
	v_pk_mul_f32 v[0:1], v[38:39], v[0:1]
	v_pk_mul_f32 v[38:39], v[108:109], v[18:19] op_sel_hi:[1,0]
	v_cvt_pk_bf16_f32 v0, v0, v1
	v_pk_mul_f32 v[2:3], v[38:39], v[2:3]
	v_pk_mul_f32 v[38:39], v[58:59], v[18:19] op_sel_hi:[1,0]
	v_cvt_pk_bf16_f32 v1, v2, v3
	v_pk_mul_f32 v[2:3], v[60:61], v[18:19] op_sel_hi:[1,0]
	s_waitcnt vmcnt(0)
	v_pk_mul_f32 v[38:39], v[38:39], v[44:45]
	v_pk_mul_f32 v[2:3], v[2:3], v[42:43]
	global_load_dwordx4 v[42:45], v140, s[66:67] offset:192
	v_cvt_pk_bf16_f32 v2, v2, v3
	v_cvt_pk_bf16_f32 v3, v38, v39
	v_pk_mul_f32 v[38:39], v[52:53], v[18:19] op_sel_hi:[1,0]
	v_permlane32_swap_b32_e32 v0, v2
	v_permlane32_swap_b32_e32 v1, v3
	s_waitcnt vmcnt(0)
	v_pk_mul_f32 v[38:39], v[38:39], v[42:43]
	v_pk_mul_f32 v[42:43], v[56:57], v[18:19] op_sel_hi:[1,0]
	v_cvt_pk_bf16_f32 v38, v38, v39
	v_pk_mul_f32 v[42:43], v[42:43], v[44:45]
	s_nop 0
	v_cvt_pk_bf16_f32 v39, v42, v43
	global_load_dwordx4 v[42:45], v140, s[66:67] offset:224
	s_waitcnt vmcnt(0)
	v_pk_mul_f32 v[40:41], v[40:41], v[42:43]
	v_pk_mul_f32 v[36:37], v[36:37], v[44:45]
	v_cvt_pk_bf16_f32 v40, v40, v41
	v_cvt_pk_bf16_f32 v41, v36, v37
	s_nop 0
	v_permlane32_swap_b32_e32 v38, v40
	v_permlane32_swap_b32_e32 v39, v41
	global_store_dwordx4 v[4:5], v[0:3], off offset:64
	global_store_dwordx4 v[4:5], v[38:41], off offset:96
	global_load_dwordx4 v[0:3], v140, s[66:67] offset:256
	v_pk_mul_f32 v[36:37], v[48:49], v[18:19] op_sel_hi:[1,0]
	s_waitcnt vmcnt(0)
	v_pk_mul_f32 v[0:1], v[36:37], v[0:1]
	v_pk_mul_f32 v[36:37], v[46:47], v[18:19] op_sel_hi:[1,0]
	v_cvt_pk_bf16_f32 v0, v0, v1
	v_pk_mul_f32 v[2:3], v[36:37], v[2:3]
	global_load_dwordx4 v[36:39], v140, s[66:67] offset:288
	v_cvt_pk_bf16_f32 v1, v2, v3
	v_pk_mul_f32 v[2:3], v[34:35], v[18:19] op_sel_hi:[1,0]
	s_waitcnt vmcnt(0)
	v_pk_mul_f32 v[32:33], v[32:33], v[38:39]
	v_pk_mul_f32 v[2:3], v[2:3], v[36:37]
	s_nop 0
	v_cvt_pk_bf16_f32 v2, v2, v3
	v_cvt_pk_bf16_f32 v3, v32, v33
	global_load_dwordx4 v[32:35], v140, s[66:67] offset:320
	v_permlane32_swap_b32_e32 v0, v2
	v_permlane32_swap_b32_e32 v1, v3
	s_waitcnt vmcnt(0)
	v_pk_mul_f32 v[30:31], v[30:31], v[32:33]
	v_pk_mul_f32 v[28:29], v[28:29], v[34:35]
	global_load_dwordx4 v[32:35], v140, s[66:67] offset:352
	v_cvt_pk_bf16_f32 v30, v30, v31
	v_cvt_pk_bf16_f32 v31, v28, v29
	global_store_dwordx4 v[4:5], v[0:3], off offset:128
	s_waitcnt vmcnt(1)
	v_pk_mul_f32 v[22:23], v[22:23], v[32:33]
	v_pk_mul_f32 v[20:21], v[20:21], v[34:35]
	v_cvt_pk_bf16_f32 v32, v22, v23
	v_cvt_pk_bf16_f32 v33, v20, v21
	s_nop 0
	v_permlane32_swap_b32_e32 v30, v32
	v_permlane32_swap_b32_e32 v31, v33
	global_store_dwordx4 v[4:5], v[30:33], off offset:160
	global_load_dwordx4 v[0:3], v140, s[66:67] offset:384
	v_pk_mul_f32 v[20:21], v[26:27], v[18:19] op_sel_hi:[1,0]
	s_waitcnt vmcnt(0)
	v_pk_mul_f32 v[0:1], v[20:21], v[0:1]
	v_pk_mul_f32 v[20:21], v[24:25], v[18:19] op_sel_hi:[1,0]
	v_cvt_pk_bf16_f32 v0, v0, v1
	v_pk_mul_f32 v[2:3], v[20:21], v[2:3]
	global_load_dwordx4 v[20:23], v140, s[66:67] offset:416
	v_cvt_pk_bf16_f32 v1, v2, v3
	v_pk_mul_f32 v[2:3], v[16:17], v[18:19] op_sel_hi:[1,0]
	s_waitcnt vmcnt(0)
	v_pk_mul_f32 v[14:15], v[14:15], v[22:23]
	v_pk_mul_f32 v[2:3], v[2:3], v[20:21]
	s_nop 0
	v_cvt_pk_bf16_f32 v2, v2, v3
	v_cvt_pk_bf16_f32 v3, v14, v15
	global_load_dwordx4 v[14:17], v140, s[66:67] offset:448
	v_permlane32_swap_b32_e32 v0, v2
	v_permlane32_swap_b32_e32 v1, v3
	s_waitcnt vmcnt(0)
	v_pk_mul_f32 v[12:13], v[12:13], v[14:15]
	v_pk_mul_f32 v[10:11], v[10:11], v[16:17]
	global_load_dwordx4 v[14:17], v140, s[66:67] offset:480
	v_cvt_pk_bf16_f32 v12, v12, v13
	v_cvt_pk_bf16_f32 v13, v10, v11
	global_store_dwordx4 v[4:5], v[0:3], off offset:192
	s_waitcnt vmcnt(1)
	v_pk_mul_f32 v[6:7], v[6:7], v[14:15]
	s_nop 0
	v_cvt_pk_bf16_f32 v14, v6, v7
	v_pk_mul_f32 v[6:7], v[8:9], v[18:19] op_sel_hi:[1,0]
	s_nop 0
	v_permlane32_swap_b32_e32 v12, v14
	v_pk_mul_f32 v[6:7], v[6:7], v[16:17]
	s_nop 0
	v_cvt_pk_bf16_f32 v15, v6, v7
	s_nop 1
	v_permlane32_swap_b32_e32 v13, v15
	global_store_dwordx4 v[4:5], v[12:15], off offset:224
	s_branch .LBB0_255
